# K-loops: all s_setprio removed
# baseline (speedup 1.0000x reference)
; #define PG8_STAGE(bufoff, gbase, voff) do { _Pragma("unroll") for (int _i = 0; _i < 2; ++_i) \
;         __builtin_amdgcn_global_load_lds((const unsigned*)((const char*)(gbase) + (voff)[_i]), (PG8_LAS unsigned*)(lds + (bufoff) + ldsw + _i * 8192), 16, 0, 0); } while (0)
; #define PG8_LDA(dst, b, h) do { _Pragma("unroll") for (int m = 0; m < 4; ++m) _Pragma("unroll") for (int k = 0; k < 2; ++k) dst[m][k] = *(const PG8_LAS bf16x8*)(lds + PG8_SA(b, h) + aoff + m * 2048 + k * 1024); } while (0)
; #define PG8_LDB(dst, b, h) do { _Pragma("unroll") for (int n = 0; n < 2; ++n) _Pragma("unroll") for (int k = 0; k < 2; ++k) dst[n][k] = *(const PG8_LAS bf16x8*)(lds + PG8_SB(b, h) + boff + n * 2048 + k * 1024); } while (0)
; #define PG8_MMA(ai, bj, At, Bt) do { __builtin_amdgcn_s_setprio(1); _Pragma("unroll") for (int m = 0; m < 4; ++m) _Pragma("unroll") for (int n = 0; n < 2; ++n) _Pragma("unroll") for (int k = 0; k < 2; ++k) \
;         acc[ai][bj][m][n] = __builtin_amdgcn_mfma_f32_16x16x32_bf16(Bt[n][k], At[m][k], acc[ai][bj][m][n], 0, 0, 0); __builtin_amdgcn_s_setprio(0); } while (0)
; #define PG8_WAIT_V(n) asm volatile("s_waitcnt vmcnt(" #n ")" ::: "memory")
; #define PG8_WAIT_L(n) asm volatile("s_waitcnt lgkmcnt(" #n ")" ::: "memory")
; #define PG8_BAR __builtin_amdgcn_s_barrier()
; template <class Epi, class Sched, bool ALIGN_EPI = false, bool SP2 = false>
; __device__ __forceinline__ void gemm_phase(PG8_LAS unsigned char* lds, const Gemm g, const Sched& S, const Epi& E, const int wid_) {
;     ...
;         for (int t = 0; t < nt; t += 2) {
;             const bool last = (t == nt - 2);
;             const char* a1 = cA + (size_t)(t + 1) * kstep;
;             const char* a2 = last ? nA : cA + (size_t)(t + 2) * kstep; const char* b2 = last ? nB : cB + (size_t)(t + 2) * kstep;
;             const char* a3 = a2 + kstep; const char* b3 = b2 + kstep;
;             if (last && has_next) S.a_ready(nxt);
;             if constexpr (SP2) {
;             PG8_LDB(B0, 0, 0); PG8_LDB(B1, 0, 1); PG8_SCHED; PG8_LDA(At, 0, 0); PG8_STAGE(PG8_SA(1, 1), a1 + hstepA, voffA);
;             PG8_WAIT_V(8); PG8_WAIT_L(0); PG8_BAR; PG8_MMA(0, 0, At, B0); PG8_MMA(0, 1, At, B1); PG8_BAR; PG8_SCHED;
;             PG8_LDA(At, 0, 1); PG8_STAGE(PG8_SB(0, 0), b2, voffB); PG8_STAGE(PG8_SB(0, 1), b2 + hstepB, voffB); PG8_STAGE(PG8_SA(0, 0), a2, voffA);
.LBB0_380:
	s_add_i32 s97, s38, 2
	s_add_u32 s98, s6, 0x80
	s_addc_u32 s39, s7, 0
	s_cmp_eq_u32 s41, s38
	s_cselect_b32 s39, s47, s39
	s_cselect_b32 s38, s46, s98
	s_cselect_b32 s99, s61, s62
	s_cselect_b32 s98, s60, s49
	s_add_i32 vcc_lo, 0, 0x14000
	v_add_u32_e32 v164, s42, v180
	v_add_u32_e32 v176, vcc_lo, v180
	ds_read_b128 v[128:131], v164
	ds_read_b128 v[132:135], v164 offset:1024
	ds_read_b128 v[136:139], v164 offset:2048
	ds_read_b128 v[164:167], v164 offset:3072
	ds_read_b128 v[168:171], v176
	ds_read_b128 v[172:175], v176 offset:1024
	ds_read_b128 v[182:185], v176 offset:2048
	ds_read_b128 v[186:189], v176 offset:3072
	v_lshl_add_u64 v[178:179], s[6:7], 0, v[162:163]
	s_add_i32 m0, s36, 0xc000
	ds_read_b128 v[190:193], v181
	ds_read_b128 v[194:197], v181 offset:1024
	ds_read_b128 v[198:201], v181 offset:2048
	ds_read_b128 v[202:205], v181 offset:3072
	ds_read_b128 v[206:209], v181 offset:4096
	ds_read_b128 v[212:215], v181 offset:5120
	ds_read_b128 v[216:219], v181 offset:6144
	ds_read_b128 v[220:223], v181 offset:7168
	global_load_lds_dwordx4 v[178:179], off
	v_lshl_add_u64 v[178:179], s[6:7], 0, v[160:161]
	s_add_i32 m0, s36, 0xe000
	s_nop 0
	global_load_lds_dwordx4 v[178:179], off
	s_waitcnt vmcnt(8)
	s_waitcnt lgkmcnt(0)
	s_barrier
	s_waitcnt lgkmcnt(0)
	v_mfma_f32_16x16x32_bf16 v[124:127], v[128:131], v[190:193], v[124:127]
	v_mfma_f32_16x16x32_bf16 v[120:123], v[136:139], v[190:193], v[120:123]
	v_mfma_f32_16x16x32_bf16 v[116:119], v[128:131], v[198:201], v[116:119]
	v_mfma_f32_16x16x32_bf16 v[112:115], v[136:139], v[198:201], v[112:115]
	v_mfma_f32_16x16x32_bf16 v[100:103], v[128:131], v[206:209], v[100:103]
	v_mfma_f32_16x16x32_bf16 v[96:99], v[136:139], v[206:209], v[96:99]
	v_mfma_f32_16x16x32_bf16 v[84:87], v[128:131], v[216:219], v[84:87]
	v_mfma_f32_16x16x32_bf16 v[80:83], v[136:139], v[216:219], v[80:83]
	v_mfma_f32_16x16x32_bf16 v[124:127], v[132:135], v[194:197], v[124:127]
	v_mfma_f32_16x16x32_bf16 v[120:123], v[164:167], v[194:197], v[120:123]
	v_mfma_f32_16x16x32_bf16 v[116:119], v[132:135], v[202:205], v[116:119]
	v_mfma_f32_16x16x32_bf16 v[112:115], v[164:167], v[202:205], v[112:115]
	v_mfma_f32_16x16x32_bf16 v[100:103], v[132:135], v[212:215], v[100:103]
	v_mfma_f32_16x16x32_bf16 v[96:99], v[164:167], v[212:215], v[96:99]
	v_mfma_f32_16x16x32_bf16 v[84:87], v[132:135], v[220:223], v[84:87]
	v_mfma_f32_16x16x32_bf16 v[80:83], v[164:167], v[220:223], v[80:83]
	v_mfma_f32_16x16x32_bf16 v[108:111], v[168:171], v[190:193], v[108:111]
	v_mfma_f32_16x16x32_bf16 v[104:107], v[182:185], v[190:193], v[104:107]
	v_mfma_f32_16x16x32_bf16 v[92:95], v[168:171], v[198:201], v[92:95]
	v_mfma_f32_16x16x32_bf16 v[88:91], v[182:185], v[198:201], v[88:91]
	v_mfma_f32_16x16x32_bf16 v[76:79], v[168:171], v[206:209], v[76:79]
	v_mfma_f32_16x16x32_bf16 v[72:75], v[182:185], v[206:209], v[72:75]
	v_mfma_f32_16x16x32_bf16 v[68:71], v[168:171], v[216:219], v[68:71]
	v_mfma_f32_16x16x32_bf16 v[64:67], v[182:185], v[216:219], v[64:67]
	v_mfma_f32_16x16x32_bf16 v[108:111], v[172:175], v[194:197], v[108:111]
	v_mfma_f32_16x16x32_bf16 v[104:107], v[186:189], v[194:197], v[104:107]
	v_mfma_f32_16x16x32_bf16 v[92:95], v[172:175], v[202:205], v[92:95]
	v_mfma_f32_16x16x32_bf16 v[88:91], v[186:189], v[202:205], v[88:91]
	v_mfma_f32_16x16x32_bf16 v[76:79], v[172:175], v[212:215], v[76:79]
	v_mfma_f32_16x16x32_bf16 v[72:75], v[186:189], v[212:215], v[72:75]
	v_mfma_f32_16x16x32_bf16 v[68:71], v[172:175], v[220:223], v[68:71]
	v_mfma_f32_16x16x32_bf16 v[64:67], v[186:189], v[220:223], v[64:67]
	s_barrier
	s_add_i32 vcc_hi, s42, s83
	v_lshl_add_u64 v[178:179], s[98:99], 0, v[142:143]
	s_mov_b32 m0, vcc_hi
	ds_read_b128 v[190:193], v181 offset:16384
	ds_read_b128 v[194:197], v181 offset:17408
	ds_read_b128 v[198:201], v181 offset:18432
	ds_read_b128 v[202:205], v181 offset:19456
	ds_read_b128 v[206:209], v181 offset:20480
	ds_read_b128 v[212:215], v181 offset:21504
	ds_read_b128 v[216:219], v181 offset:22528
	ds_read_b128 v[220:223], v181 offset:23552
	global_load_lds_dwordx4 v[178:179], off
	s_add_i32 m0, vcc_hi, 0x2000
	v_lshl_add_u64 v[224:225], s[98:99], 0, v[146:147]
	s_add_u32 s98, s98, s18
	s_addc_u32 s99, s99, 0
	s_add_i32 vcc_lo, vcc_lo, s83
	global_load_lds_dwordx4 v[224:225], off
	v_lshl_add_u64 v[226:227], s[98:99], 0, v[142:143]
	s_mov_b32 m0, vcc_lo
	v_lshl_add_u64 v[228:229], s[98:99], 0, v[146:147]
	global_load_lds_dwordx4 v[226:227], off
	s_add_i32 m0, vcc_lo, 0x2000
	v_lshl_add_u64 v[230:231], s[38:39], 0, v[140:141]
	global_load_lds_dwordx4 v[228:229], off
	s_mov_b32 m0, s36
	v_lshl_add_u64 v[232:233], s[38:39], 0, v[144:145]
	global_load_lds_dwordx4 v[230:231], off
	s_mov_b32 m0, s10
	s_nop 0
	global_load_lds_dwordx4 v[232:233], off
	s_waitcnt vmcnt(8)
	s_waitcnt lgkmcnt(0)
	s_barrier
; #define PG8_STAGE(bufoff, gbase, voff) do { _Pragma("unroll") for (int _i = 0; _i < 2; ++_i) \
;         __builtin_amdgcn_global_load_lds((const unsigned*)((const char*)(gbase) + (voff)[_i]), (PG8_LAS unsigned*)(lds + (bufoff) + ldsw + _i * 8192), 16, 0, 0); } while (0)
; #define PG8_LDA(dst, b, h) do { _Pragma("unroll") for (int m = 0; m < 4; ++m) _Pragma("unroll") for (int k = 0; k < 2; ++k) dst[m][k] = *(const PG8_LAS bf16x8*)(lds + PG8_SA(b, h) + aoff + m * 2048 + k * 1024); } while (0)
; #define PG8_LDB(dst, b, h) do { _Pragma("unroll") for (int n = 0; n < 2; ++n) _Pragma("unroll") for (int k = 0; k < 2; ++k) dst[n][k] = *(const PG8_LAS bf16x8*)(lds + PG8_SB(b, h) + boff + n * 2048 + k * 1024); } while (0)
; #define PG8_MMA(ai, bj, At, Bt) do { __builtin_amdgcn_s_setprio(1); _Pragma("unroll") for (int m = 0; m < 4; ++m) _Pragma("unroll") for (int n = 0; n < 2; ++n) _Pragma("unroll") for (int k = 0; k < 2; ++k) \
;         acc[ai][bj][m][n] = __builtin_amdgcn_mfma_f32_16x16x32_bf16(Bt[n][k], At[m][k], acc[ai][bj][m][n], 0, 0, 0); __builtin_amdgcn_s_setprio(0); } while (0)
; #define PG8_WAIT_V(n) asm volatile("s_waitcnt vmcnt(" #n ")" ::: "memory")
; #define PG8_WAIT_L(n) asm volatile("s_waitcnt lgkmcnt(" #n ")" ::: "memory")
; #define PG8_BAR __builtin_amdgcn_s_barrier()
; #define PG8_SCHED __builtin_amdgcn_sched_barrier(0)
; template <class Epi, class Sched, bool ALIGN_EPI = false, bool SP2 = false>
; __device__ __forceinline__ void gemm_phase(PG8_LAS unsigned char* lds, const Gemm g, const Sched& S, const Epi& E, const int wid_) {
;     ...
;             PG8_WAIT_V(8); PG8_WAIT_L(0); PG8_BAR; PG8_MMA(1, 0, At, B0); PG8_MMA(1, 1, At, B1); PG8_BAR; PG8_SCHED;
;             PG8_LDB(B0, 1, 0); PG8_LDB(B1, 1, 1); PG8_SCHED; PG8_LDA(At, 1, 0); PG8_STAGE(PG8_SA(0, 1), a2 + hstepA, voffA);
;             PG8_WAIT_V(8); PG8_WAIT_L(0); PG8_BAR; PG8_MMA(0, 0, At, B0); PG8_MMA(0, 1, At, B1); PG8_BAR; PG8_SCHED;
	s_waitcnt lgkmcnt(0)
	v_mfma_f32_16x16x32_bf16 v[60:63], v[128:131], v[190:193], v[60:63]
	v_mfma_f32_16x16x32_bf16 v[56:59], v[136:139], v[190:193], v[56:59]
	v_mfma_f32_16x16x32_bf16 v[52:55], v[128:131], v[198:201], v[52:55]
	v_mfma_f32_16x16x32_bf16 v[48:51], v[136:139], v[198:201], v[48:51]
	v_mfma_f32_16x16x32_bf16 v[36:39], v[128:131], v[206:209], v[36:39]
	v_mfma_f32_16x16x32_bf16 v[32:35], v[136:139], v[206:209], v[32:35]
	v_mfma_f32_16x16x32_bf16 v[20:23], v[128:131], v[216:219], v[20:23]
	v_mfma_f32_16x16x32_bf16 v[16:19], v[136:139], v[216:219], v[16:19]
	v_mfma_f32_16x16x32_bf16 v[60:63], v[132:135], v[194:197], v[60:63]
	v_mfma_f32_16x16x32_bf16 v[56:59], v[164:167], v[194:197], v[56:59]
	v_mfma_f32_16x16x32_bf16 v[52:55], v[132:135], v[202:205], v[52:55]
	v_mfma_f32_16x16x32_bf16 v[48:51], v[164:167], v[202:205], v[48:51]
	v_mfma_f32_16x16x32_bf16 v[36:39], v[132:135], v[212:215], v[36:39]
	v_mfma_f32_16x16x32_bf16 v[32:35], v[164:167], v[212:215], v[32:35]
	v_mfma_f32_16x16x32_bf16 v[20:23], v[132:135], v[220:223], v[20:23]
	v_mfma_f32_16x16x32_bf16 v[16:19], v[164:167], v[220:223], v[16:19]
	v_mfma_f32_16x16x32_bf16 v[44:47], v[168:171], v[190:193], v[44:47]
	v_mfma_f32_16x16x32_bf16 v[40:43], v[182:185], v[190:193], v[40:43]
	v_mfma_f32_16x16x32_bf16 v[28:31], v[168:171], v[198:201], v[28:31]
	v_mfma_f32_16x16x32_bf16 v[24:27], v[182:185], v[198:201], v[24:27]
	v_mfma_f32_16x16x32_bf16 v[12:15], v[168:171], v[206:209], v[12:15]
	v_mfma_f32_16x16x32_bf16 v[8:11], v[182:185], v[206:209], v[8:11]
	v_mfma_f32_16x16x32_bf16 v[4:7], v[168:171], v[216:219], v[4:7]
	v_mfma_f32_16x16x32_bf16 v[0:3], v[182:185], v[216:219], v[0:3]
	v_mfma_f32_16x16x32_bf16 v[44:47], v[172:175], v[194:197], v[44:47]
	v_mfma_f32_16x16x32_bf16 v[40:43], v[186:189], v[194:197], v[40:43]
	v_mfma_f32_16x16x32_bf16 v[28:31], v[172:175], v[202:205], v[28:31]
	v_mfma_f32_16x16x32_bf16 v[24:27], v[186:189], v[202:205], v[24:27]
	v_mfma_f32_16x16x32_bf16 v[12:15], v[172:175], v[212:215], v[12:15]
	v_mfma_f32_16x16x32_bf16 v[8:11], v[186:189], v[212:215], v[8:11]
	v_mfma_f32_16x16x32_bf16 v[4:7], v[172:175], v[220:223], v[4:7]
	v_mfma_f32_16x16x32_bf16 v[0:3], v[186:189], v[220:223], v[0:3]
	s_barrier
	s_add_i32 s98, 0, 0x18000
	s_add_i32 s99, 0, 0x1c000
	v_add_u32_e32 v164, s98, v180
	v_add_u32_e32 v176, s99, v180
	ds_read_b128 v[128:131], v164
	ds_read_b128 v[132:135], v164 offset:1024
	ds_read_b128 v[136:139], v164 offset:2048
	ds_read_b128 v[164:167], v164 offset:3072
	ds_read_b128 v[168:171], v176
	ds_read_b128 v[172:175], v176 offset:1024
	ds_read_b128 v[182:185], v176 offset:2048
	ds_read_b128 v[186:189], v176 offset:3072
	s_add_u32 s38, s38, s88
	s_addc_u32 s39, s39, 0
	s_mov_b32 m0, s11
	v_lshl_add_u64 v[234:235], s[38:39], 0, v[140:141]
	ds_read_b128 v[190:193], v181 offset:32768
	ds_read_b128 v[194:197], v181 offset:33792
	ds_read_b128 v[198:201], v181 offset:34816
	ds_read_b128 v[202:205], v181 offset:35840
	ds_read_b128 v[206:209], v181 offset:36864
	ds_read_b128 v[212:215], v181 offset:37888
	ds_read_b128 v[216:219], v181 offset:38912
	ds_read_b128 v[220:223], v181 offset:39936
	global_load_lds_dwordx4 v[234:235], off
	v_lshl_add_u64 v[234:235], s[38:39], 0, v[144:145]
	s_mov_b32 m0, s55
	s_nop 0
	global_load_lds_dwordx4 v[234:235], off
	s_waitcnt vmcnt(8)
	s_waitcnt lgkmcnt(0)
	s_barrier
	s_waitcnt lgkmcnt(0)
	v_mfma_f32_16x16x32_bf16 v[124:127], v[128:131], v[190:193], v[124:127]
	v_mfma_f32_16x16x32_bf16 v[120:123], v[136:139], v[190:193], v[120:123]
	v_mfma_f32_16x16x32_bf16 v[116:119], v[128:131], v[198:201], v[116:119]
	v_mfma_f32_16x16x32_bf16 v[112:115], v[136:139], v[198:201], v[112:115]
	v_mfma_f32_16x16x32_bf16 v[100:103], v[128:131], v[206:209], v[100:103]
	v_mfma_f32_16x16x32_bf16 v[96:99], v[136:139], v[206:209], v[96:99]
	v_mfma_f32_16x16x32_bf16 v[84:87], v[128:131], v[216:219], v[84:87]
	v_mfma_f32_16x16x32_bf16 v[80:83], v[136:139], v[216:219], v[80:83]
	v_mfma_f32_16x16x32_bf16 v[124:127], v[132:135], v[194:197], v[124:127]
	v_mfma_f32_16x16x32_bf16 v[120:123], v[164:167], v[194:197], v[120:123]
	v_mfma_f32_16x16x32_bf16 v[116:119], v[132:135], v[202:205], v[116:119]
	v_mfma_f32_16x16x32_bf16 v[112:115], v[164:167], v[202:205], v[112:115]
	v_mfma_f32_16x16x32_bf16 v[100:103], v[132:135], v[212:215], v[100:103]
	v_mfma_f32_16x16x32_bf16 v[96:99], v[164:167], v[212:215], v[96:99]
	v_mfma_f32_16x16x32_bf16 v[84:87], v[132:135], v[220:223], v[84:87]
	v_mfma_f32_16x16x32_bf16 v[80:83], v[164:167], v[220:223], v[80:83]
	v_mfma_f32_16x16x32_bf16 v[108:111], v[168:171], v[190:193], v[108:111]
	v_mfma_f32_16x16x32_bf16 v[104:107], v[182:185], v[190:193], v[104:107]
	v_mfma_f32_16x16x32_bf16 v[92:95], v[168:171], v[198:201], v[92:95]
	v_mfma_f32_16x16x32_bf16 v[88:91], v[182:185], v[198:201], v[88:91]
	v_mfma_f32_16x16x32_bf16 v[76:79], v[168:171], v[206:209], v[76:79]
	v_mfma_f32_16x16x32_bf16 v[72:75], v[182:185], v[206:209], v[72:75]
	v_mfma_f32_16x16x32_bf16 v[68:71], v[168:171], v[216:219], v[68:71]
	v_mfma_f32_16x16x32_bf16 v[64:67], v[182:185], v[216:219], v[64:67]
	v_mfma_f32_16x16x32_bf16 v[108:111], v[172:175], v[194:197], v[108:111]
	v_mfma_f32_16x16x32_bf16 v[104:107], v[186:189], v[194:197], v[104:107]
	v_mfma_f32_16x16x32_bf16 v[92:95], v[172:175], v[202:205], v[92:95]
	v_mfma_f32_16x16x32_bf16 v[88:91], v[186:189], v[202:205], v[88:91]
	v_mfma_f32_16x16x32_bf16 v[76:79], v[172:175], v[212:215], v[76:79]
	v_mfma_f32_16x16x32_bf16 v[72:75], v[186:189], v[212:215], v[72:75]
	v_mfma_f32_16x16x32_bf16 v[68:71], v[172:175], v[220:223], v[68:71]
	v_mfma_f32_16x16x32_bf16 v[64:67], v[186:189], v[220:223], v[64:67]
	s_barrier
; #define PG8_STAGE(bufoff, gbase, voff) do { _Pragma("unroll") for (int _i = 0; _i < 2; ++_i) \
;         __builtin_amdgcn_global_load_lds((const unsigned*)((const char*)(gbase) + (voff)[_i]), (PG8_LAS unsigned*)(lds + (bufoff) + ldsw + _i * 8192), 16, 0, 0); } while (0)
; #define PG8_LDA(dst, b, h) do { _Pragma("unroll") for (int m = 0; m < 4; ++m) _Pragma("unroll") for (int k = 0; k < 2; ++k) dst[m][k] = *(const PG8_LAS bf16x8*)(lds + PG8_SA(b, h) + aoff + m * 2048 + k * 1024); } while (0)
; #define PG8_MMA(ai, bj, At, Bt) do { __builtin_amdgcn_s_setprio(1); _Pragma("unroll") for (int m = 0; m < 4; ++m) _Pragma("unroll") for (int n = 0; n < 2; ++n) _Pragma("unroll") for (int k = 0; k < 2; ++k) \
;         acc[ai][bj][m][n] = __builtin_amdgcn_mfma_f32_16x16x32_bf16(Bt[n][k], At[m][k], acc[ai][bj][m][n], 0, 0, 0); __builtin_amdgcn_s_setprio(0); } while (0)
; #define PG8_WAIT_V(n) asm volatile("s_waitcnt vmcnt(" #n ")" ::: "memory")
; #define PG8_WAIT_L(n) asm volatile("s_waitcnt lgkmcnt(" #n ")" ::: "memory")
; #define PG8_BAR __builtin_amdgcn_s_barrier()
; #define PG8_SCHED __builtin_amdgcn_sched_barrier(0)
; template <class Epi, class Sched, bool ALIGN_EPI = false, bool SP2 = false>
; __device__ __forceinline__ void gemm_phase(PG8_LAS unsigned char* lds, const Gemm g, const Sched& S, const Epi& E, const int wid_) {
;     ...
;             PG8_LDA(At, 1, 1); PG8_STAGE(PG8_SB(1, 0), b3, voffB); PG8_STAGE(PG8_SB(1, 1), b3 + hstepB, voffB); PG8_STAGE(PG8_SA(1, 0), a3, voffA);
;             PG8_WAIT_V(8); PG8_WAIT_L(0); PG8_BAR; PG8_MMA(1, 0, At, B0); PG8_MMA(1, 1, At, B1); PG8_BAR; PG8_SCHED;
;     ...
;         if constexpr (ALIGN_EPI) { if (wr == 0) PG8_BAR; }
	s_add_i32 s38, s98, s83
	v_lshl_add_u64 v[178:179], v[178:179], 0, s[66:67]
	s_mov_b32 m0, s38
	ds_read_b128 v[190:193], v181 offset:49152
	ds_read_b128 v[194:197], v181 offset:50176
	ds_read_b128 v[198:201], v181 offset:51200
	ds_read_b128 v[202:205], v181 offset:52224
	ds_read_b128 v[206:209], v181 offset:53248
	ds_read_b128 v[212:215], v181 offset:54272
	ds_read_b128 v[216:219], v181 offset:55296
	ds_read_b128 v[220:223], v181 offset:56320
	global_load_lds_dwordx4 v[178:179], off
	v_lshl_add_u64 v[178:179], v[224:225], 0, s[66:67]
	s_add_i32 m0, s38, 0x2000
	s_add_i32 s38, s99, s83
	global_load_lds_dwordx4 v[178:179], off
	v_lshl_add_u64 v[178:179], v[226:227], 0, s[66:67]
	s_mov_b32 m0, s38
	s_nop 0
	global_load_lds_dwordx4 v[178:179], off
	v_lshl_add_u64 v[178:179], v[228:229], 0, s[66:67]
	s_add_i32 m0, s38, 0x2000
	s_nop 0
	global_load_lds_dwordx4 v[178:179], off
	v_lshl_add_u64 v[178:179], v[230:231], 0, s[66:67]
	s_mov_b32 m0, s33
	s_nop 0
	global_load_lds_dwordx4 v[178:179], off
	v_lshl_add_u64 v[178:179], v[232:233], 0, s[66:67]
	s_mov_b32 m0, s52
	s_nop 0
	global_load_lds_dwordx4 v[178:179], off
	s_waitcnt vmcnt(8)
	s_waitcnt lgkmcnt(0)
	s_barrier
	s_waitcnt lgkmcnt(0)
	v_mfma_f32_16x16x32_bf16 v[60:63], v[128:131], v[190:193], v[60:63]
	v_mfma_f32_16x16x32_bf16 v[56:59], v[136:139], v[190:193], v[56:59]
	v_mfma_f32_16x16x32_bf16 v[52:55], v[128:131], v[198:201], v[52:55]
	v_mfma_f32_16x16x32_bf16 v[48:51], v[136:139], v[198:201], v[48:51]
	v_mfma_f32_16x16x32_bf16 v[36:39], v[128:131], v[206:209], v[36:39]
	v_mfma_f32_16x16x32_bf16 v[32:35], v[136:139], v[206:209], v[32:35]
	v_mfma_f32_16x16x32_bf16 v[20:23], v[128:131], v[216:219], v[20:23]
	v_mfma_f32_16x16x32_bf16 v[16:19], v[136:139], v[216:219], v[16:19]
	v_mfma_f32_16x16x32_bf16 v[60:63], v[132:135], v[194:197], v[60:63]
	v_mfma_f32_16x16x32_bf16 v[56:59], v[164:167], v[194:197], v[56:59]
	v_mfma_f32_16x16x32_bf16 v[52:55], v[132:135], v[202:205], v[52:55]
	v_mfma_f32_16x16x32_bf16 v[48:51], v[164:167], v[202:205], v[48:51]
	v_mfma_f32_16x16x32_bf16 v[36:39], v[132:135], v[212:215], v[36:39]
	v_mfma_f32_16x16x32_bf16 v[32:35], v[164:167], v[212:215], v[32:35]
	v_mfma_f32_16x16x32_bf16 v[20:23], v[132:135], v[220:223], v[20:23]
	v_mfma_f32_16x16x32_bf16 v[16:19], v[164:167], v[220:223], v[16:19]
	v_mfma_f32_16x16x32_bf16 v[44:47], v[168:171], v[190:193], v[44:47]
	v_mfma_f32_16x16x32_bf16 v[40:43], v[182:185], v[190:193], v[40:43]
	v_mfma_f32_16x16x32_bf16 v[28:31], v[168:171], v[198:201], v[28:31]
	v_mfma_f32_16x16x32_bf16 v[24:27], v[182:185], v[198:201], v[24:27]
	v_mfma_f32_16x16x32_bf16 v[12:15], v[168:171], v[206:209], v[12:15]
	v_mfma_f32_16x16x32_bf16 v[8:11], v[182:185], v[206:209], v[8:11]
	v_mfma_f32_16x16x32_bf16 v[4:7], v[168:171], v[216:219], v[4:7]
	v_mfma_f32_16x16x32_bf16 v[0:3], v[182:185], v[216:219], v[0:3]
	v_mfma_f32_16x16x32_bf16 v[44:47], v[172:175], v[194:197], v[44:47]
	v_mfma_f32_16x16x32_bf16 v[40:43], v[186:189], v[194:197], v[40:43]
	v_mfma_f32_16x16x32_bf16 v[28:31], v[172:175], v[202:205], v[28:31]
	v_mfma_f32_16x16x32_bf16 v[24:27], v[186:189], v[202:205], v[24:27]
	v_mfma_f32_16x16x32_bf16 v[12:15], v[172:175], v[212:215], v[12:15]
	v_mfma_f32_16x16x32_bf16 v[8:11], v[186:189], v[212:215], v[8:11]
	v_mfma_f32_16x16x32_bf16 v[4:7], v[172:175], v[220:223], v[4:7]
	v_mfma_f32_16x16x32_bf16 v[0:3], v[186:189], v[220:223], v[0:3]
	s_barrier
	s_add_u32 s49, s49, 0x100
	s_addc_u32 s62, s62, 0
	s_add_u32 s6, s6, 0x100
	s_addc_u32 s7, s7, 0
	s_cmp_ge_u32 s97, s71
	s_mov_b32 s38, s97
	s_cbranch_scc0 .LBB0_380
	s_and_b64 vcc, exec, s[94:95]
	s_cbranch_vccz .LBB0_384
	s_barrier
	v_lshl_add_u32 v164, s48, 8, v153
	s_cmp_lt_i32 s37, 2
	s_mov_b64 s[6:7], -1
	s_cbranch_scc0 .LBB0_385

; #define PG8_STAGE(bufoff, gbase, voff) do { _Pragma("unroll") for (int _i = 0; _i < 2; ++_i) \
;         __builtin_amdgcn_global_load_lds((const unsigned*)((const char*)(gbase) + (voff)[_i]), (PG8_LAS unsigned*)(lds + (bufoff) + ldsw + _i * 8192), 16, 0, 0); } while (0)
; #define PG8_LDA(dst, b, h) do { _Pragma("unroll") for (int m = 0; m < 4; ++m) _Pragma("unroll") for (int k = 0; k < 2; ++k) dst[m][k] = *(const PG8_LAS bf16x8*)(lds + PG8_SA(b, h) + aoff + m * 2048 + k * 1024); } while (0)
; #define PG8_LDB(dst, b, h) do { _Pragma("unroll") for (int n = 0; n < 2; ++n) _Pragma("unroll") for (int k = 0; k < 2; ++k) dst[n][k] = *(const PG8_LAS bf16x8*)(lds + PG8_SB(b, h) + boff + n * 2048 + k * 1024); } while (0)
; #define PG8_MMA(ai, bj, At, Bt) do { __builtin_amdgcn_s_setprio(1); _Pragma("unroll") for (int m = 0; m < 4; ++m) _Pragma("unroll") for (int n = 0; n < 2; ++n) _Pragma("unroll") for (int k = 0; k < 2; ++k) \
;         acc[ai][bj][m][n] = __builtin_amdgcn_mfma_f32_16x16x32_bf16(Bt[n][k], At[m][k], acc[ai][bj][m][n], 0, 0, 0); __builtin_amdgcn_s_setprio(0); } while (0)
; #define PG8_WAIT_V(n) asm volatile("s_waitcnt vmcnt(" #n ")" ::: "memory")
; #define PG8_WAIT_L(n) asm volatile("s_waitcnt lgkmcnt(" #n ")" ::: "memory")
; #define PG8_BAR __builtin_amdgcn_s_barrier()
; template <class Epi, class Sched, bool ALIGN_EPI = false, bool SP2 = false>
; __device__ __forceinline__ void gemm_phase(PG8_LAS unsigned char* lds, const Gemm g, const Sched& S, const Epi& E, const int wid_) {
;     ...
;         for (int t = 0; t < nt; t += 2) {
;             const bool last = (t == nt - 2);
;             const char* a1 = cA + (size_t)(t + 1) * kstep;
;             const char* a2 = last ? nA : cA + (size_t)(t + 2) * kstep; const char* b2 = last ? nB : cB + (size_t)(t + 2) * kstep;
;             const char* a3 = a2 + kstep; const char* b3 = b2 + kstep;
;             if (last && has_next) S.a_ready(nxt);
;             if constexpr (SP2) {
;             PG8_LDB(B0, 0, 0); PG8_LDB(B1, 0, 1); PG8_SCHED; PG8_LDA(At, 0, 0); PG8_STAGE(PG8_SA(1, 1), a1 + hstepA, voffA);
;             PG8_WAIT_V(8); PG8_WAIT_L(0); PG8_BAR; PG8_MMA(0, 0, At, B0); PG8_MMA(0, 1, At, B1); PG8_BAR; PG8_SCHED;
;             PG8_LDA(At, 0, 1); PG8_STAGE(PG8_SB(0, 0), b2, voffB); PG8_STAGE(PG8_SB(0, 1), b2 + hstepB, voffB); PG8_STAGE(PG8_SA(0, 0), a2, voffA);
.LBB0_614:
	s_add_i32 s38, s8, 2
	s_add_u32 s39, s6, 0x80
	s_addc_u32 s9, s7, 0
	s_cmp_eq_u32 s80, s8
	s_cselect_b32 s9, s73, s9
	s_cselect_b32 s8, s72, s39
	s_cselect_b32 s87, s75, s76
	s_cselect_b32 s86, s74, s11
	s_add_i32 s39, 0, 0x14000
	v_add_u32_e32 v132, s42, v246
	v_add_u32_e32 v156, s39, v246
	ds_read_b128 v[104:107], v132
	ds_read_b128 v[112:115], v132 offset:1024
	ds_read_b128 v[124:127], v132 offset:2048
	ds_read_b128 v[132:135], v132 offset:3072
	ds_read_b128 v[144:147], v156
	ds_read_b128 v[148:151], v156 offset:1024
	ds_read_b128 v[152:155], v156 offset:2048
	ds_read_b128 v[156:159], v156 offset:3072
	v_lshl_add_u64 v[194:195], s[6:7], 0, v[216:217]
	s_add_i32 m0, s41, 0xc000
	ds_read_b128 v[160:163], v247
	ds_read_b128 v[164:167], v247 offset:1024
	ds_read_b128 v[168:171], v247 offset:2048
	ds_read_b128 v[172:175], v247 offset:3072
	ds_read_b128 v[178:181], v247 offset:4096
	ds_read_b128 v[182:185], v247 offset:5120
	ds_read_b128 v[186:189], v247 offset:6144
	ds_read_b128 v[190:193], v247 offset:7168
	global_load_lds_dwordx4 v[194:195], off
	v_lshl_add_u64 v[194:195], s[6:7], 0, v[214:215]
	s_add_i32 m0, s41, 0xe000
	s_nop 0
	global_load_lds_dwordx4 v[194:195], off
	s_waitcnt vmcnt(8)
	s_waitcnt lgkmcnt(0)
	s_barrier
	s_waitcnt lgkmcnt(0)
	v_mfma_f32_16x16x32_bf16 v[140:143], v[104:107], v[160:163], v[140:143]
	v_mfma_f32_16x16x32_bf16 v[136:139], v[124:127], v[160:163], v[136:139]
	v_mfma_f32_16x16x32_bf16 v[116:119], v[104:107], v[168:171], v[116:119]
	v_mfma_f32_16x16x32_bf16 v[108:111], v[124:127], v[168:171], v[108:111]
	v_mfma_f32_16x16x32_bf16 v[92:95], v[104:107], v[178:181], v[92:95]
	v_mfma_f32_16x16x32_bf16 v[88:91], v[124:127], v[178:181], v[88:91]
	v_mfma_f32_16x16x32_bf16 v[76:79], v[104:107], v[186:189], v[76:79]
	v_mfma_f32_16x16x32_bf16 v[72:75], v[124:127], v[186:189], v[72:75]
	v_mfma_f32_16x16x32_bf16 v[140:143], v[112:115], v[164:167], v[140:143]
	v_mfma_f32_16x16x32_bf16 v[136:139], v[132:135], v[164:167], v[136:139]
	v_mfma_f32_16x16x32_bf16 v[116:119], v[112:115], v[172:175], v[116:119]
	v_mfma_f32_16x16x32_bf16 v[108:111], v[132:135], v[172:175], v[108:111]
	v_mfma_f32_16x16x32_bf16 v[92:95], v[112:115], v[182:185], v[92:95]
	v_mfma_f32_16x16x32_bf16 v[88:91], v[132:135], v[182:185], v[88:91]
	v_mfma_f32_16x16x32_bf16 v[76:79], v[112:115], v[190:193], v[76:79]
	v_mfma_f32_16x16x32_bf16 v[72:75], v[132:135], v[190:193], v[72:75]
	v_mfma_f32_16x16x32_bf16 v[128:131], v[144:147], v[160:163], v[128:131]
	v_mfma_f32_16x16x32_bf16 v[120:123], v[152:155], v[160:163], v[120:123]
	v_mfma_f32_16x16x32_bf16 v[100:103], v[144:147], v[168:171], v[100:103]
	v_mfma_f32_16x16x32_bf16 v[96:99], v[152:155], v[168:171], v[96:99]
	v_mfma_f32_16x16x32_bf16 v[84:87], v[144:147], v[178:181], v[84:87]
	v_mfma_f32_16x16x32_bf16 v[80:83], v[152:155], v[178:181], v[80:83]
	v_mfma_f32_16x16x32_bf16 v[68:71], v[144:147], v[186:189], v[68:71]
	v_mfma_f32_16x16x32_bf16 v[64:67], v[152:155], v[186:189], v[64:67]
	v_mfma_f32_16x16x32_bf16 v[128:131], v[148:151], v[164:167], v[128:131]
	v_mfma_f32_16x16x32_bf16 v[120:123], v[156:159], v[164:167], v[120:123]
	v_mfma_f32_16x16x32_bf16 v[100:103], v[148:151], v[172:175], v[100:103]
	v_mfma_f32_16x16x32_bf16 v[96:99], v[156:159], v[172:175], v[96:99]
	v_mfma_f32_16x16x32_bf16 v[84:87], v[148:151], v[182:185], v[84:87]
	v_mfma_f32_16x16x32_bf16 v[80:83], v[156:159], v[182:185], v[80:83]
	v_mfma_f32_16x16x32_bf16 v[68:71], v[148:151], v[190:193], v[68:71]
	v_mfma_f32_16x16x32_bf16 v[64:67], v[156:159], v[190:193], v[64:67]
	s_barrier
	s_add_i32 s85, s42, s33
	v_lshl_add_u64 v[194:195], s[86:87], 0, v[176:177]
	s_mov_b32 m0, s85
	ds_read_b128 v[160:163], v247 offset:16384
	ds_read_b128 v[164:167], v247 offset:17408
	ds_read_b128 v[168:171], v247 offset:18432
	ds_read_b128 v[172:175], v247 offset:19456
	ds_read_b128 v[178:181], v247 offset:20480
	ds_read_b128 v[182:185], v247 offset:21504
	ds_read_b128 v[186:189], v247 offset:22528
	ds_read_b128 v[190:193], v247 offset:23552
	global_load_lds_dwordx4 v[194:195], off
	s_add_i32 m0, s85, 0x2000
	v_lshl_add_u64 v[196:197], s[86:87], 0, v[202:203]
	s_add_u32 s86, s86, s22
	s_addc_u32 s87, s87, 0
	s_add_i32 s39, s39, s33
	global_load_lds_dwordx4 v[196:197], off
	v_lshl_add_u64 v[198:199], s[86:87], 0, v[176:177]
	s_mov_b32 m0, s39
	v_lshl_add_u64 v[200:201], s[86:87], 0, v[202:203]
	global_load_lds_dwordx4 v[198:199], off
	s_add_i32 m0, s39, 0x2000
	v_lshl_add_u64 v[218:219], s[8:9], 0, v[206:207]
	global_load_lds_dwordx4 v[200:201], off
	s_mov_b32 m0, s41
	v_lshl_add_u64 v[220:221], s[8:9], 0, v[204:205]
	global_load_lds_dwordx4 v[218:219], off
	s_mov_b32 m0, s43
	s_nop 0
	global_load_lds_dwordx4 v[220:221], off
	s_waitcnt vmcnt(8)
	s_waitcnt lgkmcnt(0)
	s_barrier
; #define PG8_STAGE(bufoff, gbase, voff) do { _Pragma("unroll") for (int _i = 0; _i < 2; ++_i) \
;         __builtin_amdgcn_global_load_lds((const unsigned*)((const char*)(gbase) + (voff)[_i]), (PG8_LAS unsigned*)(lds + (bufoff) + ldsw + _i * 8192), 16, 0, 0); } while (0)
; #define PG8_LDA(dst, b, h) do { _Pragma("unroll") for (int m = 0; m < 4; ++m) _Pragma("unroll") for (int k = 0; k < 2; ++k) dst[m][k] = *(const PG8_LAS bf16x8*)(lds + PG8_SA(b, h) + aoff + m * 2048 + k * 1024); } while (0)
; #define PG8_LDB(dst, b, h) do { _Pragma("unroll") for (int n = 0; n < 2; ++n) _Pragma("unroll") for (int k = 0; k < 2; ++k) dst[n][k] = *(const PG8_LAS bf16x8*)(lds + PG8_SB(b, h) + boff + n * 2048 + k * 1024); } while (0)
; #define PG8_MMA(ai, bj, At, Bt) do { __builtin_amdgcn_s_setprio(1); _Pragma("unroll") for (int m = 0; m < 4; ++m) _Pragma("unroll") for (int n = 0; n < 2; ++n) _Pragma("unroll") for (int k = 0; k < 2; ++k) \
;         acc[ai][bj][m][n] = __builtin_amdgcn_mfma_f32_16x16x32_bf16(Bt[n][k], At[m][k], acc[ai][bj][m][n], 0, 0, 0); __builtin_amdgcn_s_setprio(0); } while (0)
; #define PG8_WAIT_V(n) asm volatile("s_waitcnt vmcnt(" #n ")" ::: "memory")
; #define PG8_WAIT_L(n) asm volatile("s_waitcnt lgkmcnt(" #n ")" ::: "memory")
; #define PG8_BAR __builtin_amdgcn_s_barrier()
; #define PG8_SCHED __builtin_amdgcn_sched_barrier(0)
; template <class Epi, class Sched, bool ALIGN_EPI = false, bool SP2 = false>
; __device__ __forceinline__ void gemm_phase(PG8_LAS unsigned char* lds, const Gemm g, const Sched& S, const Epi& E, const int wid_) {
;     ...
;             PG8_WAIT_V(8); PG8_WAIT_L(0); PG8_BAR; PG8_MMA(1, 0, At, B0); PG8_MMA(1, 1, At, B1); PG8_BAR; PG8_SCHED;
;             PG8_LDB(B0, 1, 0); PG8_LDB(B1, 1, 1); PG8_SCHED; PG8_LDA(At, 1, 0); PG8_STAGE(PG8_SA(0, 1), a2 + hstepA, voffA);
;             PG8_WAIT_V(8); PG8_WAIT_L(0); PG8_BAR; PG8_MMA(0, 0, At, B0); PG8_MMA(0, 1, At, B1); PG8_BAR; PG8_SCHED;
	s_waitcnt lgkmcnt(0)
	v_mfma_f32_16x16x32_bf16 v[60:63], v[104:107], v[160:163], v[60:63]
	v_mfma_f32_16x16x32_bf16 v[56:59], v[124:127], v[160:163], v[56:59]
	v_mfma_f32_16x16x32_bf16 v[44:47], v[104:107], v[168:171], v[44:47]
	v_mfma_f32_16x16x32_bf16 v[40:43], v[124:127], v[168:171], v[40:43]
	v_mfma_f32_16x16x32_bf16 v[28:31], v[104:107], v[178:181], v[28:31]
	v_mfma_f32_16x16x32_bf16 v[24:27], v[124:127], v[178:181], v[24:27]
	v_mfma_f32_16x16x32_bf16 v[12:15], v[104:107], v[186:189], v[12:15]
	v_mfma_f32_16x16x32_bf16 v[8:11], v[124:127], v[186:189], v[8:11]
	v_mfma_f32_16x16x32_bf16 v[60:63], v[112:115], v[164:167], v[60:63]
	v_mfma_f32_16x16x32_bf16 v[56:59], v[132:135], v[164:167], v[56:59]
	v_mfma_f32_16x16x32_bf16 v[44:47], v[112:115], v[172:175], v[44:47]
	v_mfma_f32_16x16x32_bf16 v[40:43], v[132:135], v[172:175], v[40:43]
	v_mfma_f32_16x16x32_bf16 v[28:31], v[112:115], v[182:185], v[28:31]
	v_mfma_f32_16x16x32_bf16 v[24:27], v[132:135], v[182:185], v[24:27]
	v_mfma_f32_16x16x32_bf16 v[12:15], v[112:115], v[190:193], v[12:15]
	v_mfma_f32_16x16x32_bf16 v[8:11], v[132:135], v[190:193], v[8:11]
	v_mfma_f32_16x16x32_bf16 v[52:55], v[144:147], v[160:163], v[52:55]
	v_mfma_f32_16x16x32_bf16 v[48:51], v[152:155], v[160:163], v[48:51]
	v_mfma_f32_16x16x32_bf16 v[36:39], v[144:147], v[168:171], v[36:39]
	v_mfma_f32_16x16x32_bf16 v[32:35], v[152:155], v[168:171], v[32:35]
	v_mfma_f32_16x16x32_bf16 v[20:23], v[144:147], v[178:181], v[20:23]
	v_mfma_f32_16x16x32_bf16 v[16:19], v[152:155], v[178:181], v[16:19]
	v_mfma_f32_16x16x32_bf16 v[4:7], v[144:147], v[186:189], v[4:7]
	v_mfma_f32_16x16x32_bf16 v[0:3], v[152:155], v[186:189], v[0:3]
	v_mfma_f32_16x16x32_bf16 v[52:55], v[148:151], v[164:167], v[52:55]
	v_mfma_f32_16x16x32_bf16 v[48:51], v[156:159], v[164:167], v[48:51]
	v_mfma_f32_16x16x32_bf16 v[36:39], v[148:151], v[172:175], v[36:39]
	v_mfma_f32_16x16x32_bf16 v[32:35], v[156:159], v[172:175], v[32:35]
	v_mfma_f32_16x16x32_bf16 v[20:23], v[148:151], v[182:185], v[20:23]
	v_mfma_f32_16x16x32_bf16 v[16:19], v[156:159], v[182:185], v[16:19]
	v_mfma_f32_16x16x32_bf16 v[4:7], v[148:151], v[190:193], v[4:7]
	v_mfma_f32_16x16x32_bf16 v[0:3], v[156:159], v[190:193], v[0:3]
	s_barrier
	s_add_i32 s39, 0, 0x18000
	s_add_i32 s85, 0, 0x1c000
	v_add_u32_e32 v132, s39, v246
	v_add_u32_e32 v156, s85, v246
	ds_read_b128 v[104:107], v132
	ds_read_b128 v[112:115], v132 offset:1024
	ds_read_b128 v[124:127], v132 offset:2048
	ds_read_b128 v[132:135], v132 offset:3072
	ds_read_b128 v[144:147], v156
	ds_read_b128 v[148:151], v156 offset:1024
	ds_read_b128 v[152:155], v156 offset:2048
	ds_read_b128 v[156:159], v156 offset:3072
	s_add_u32 s8, s8, s22
	s_addc_u32 s9, s9, 0
	s_mov_b32 m0, s46
	v_lshl_add_u64 v[222:223], s[8:9], 0, v[206:207]
	ds_read_b128 v[160:163], v247 offset:32768
	ds_read_b128 v[164:167], v247 offset:33792
	ds_read_b128 v[168:171], v247 offset:34816
	ds_read_b128 v[172:175], v247 offset:35840
	ds_read_b128 v[178:181], v247 offset:36864
	ds_read_b128 v[182:185], v247 offset:37888
	ds_read_b128 v[186:189], v247 offset:38912
	ds_read_b128 v[190:193], v247 offset:39936
	global_load_lds_dwordx4 v[222:223], off
	v_lshl_add_u64 v[222:223], s[8:9], 0, v[204:205]
	s_mov_b32 m0, s47
	s_nop 0
	global_load_lds_dwordx4 v[222:223], off
	s_waitcnt vmcnt(8)
	s_waitcnt lgkmcnt(0)
	s_barrier
	s_waitcnt lgkmcnt(0)
	v_mfma_f32_16x16x32_bf16 v[140:143], v[104:107], v[160:163], v[140:143]
	v_mfma_f32_16x16x32_bf16 v[136:139], v[124:127], v[160:163], v[136:139]
	v_mfma_f32_16x16x32_bf16 v[116:119], v[104:107], v[168:171], v[116:119]
	v_mfma_f32_16x16x32_bf16 v[108:111], v[124:127], v[168:171], v[108:111]
	v_mfma_f32_16x16x32_bf16 v[92:95], v[104:107], v[178:181], v[92:95]
	v_mfma_f32_16x16x32_bf16 v[88:91], v[124:127], v[178:181], v[88:91]
	v_mfma_f32_16x16x32_bf16 v[76:79], v[104:107], v[186:189], v[76:79]
	v_mfma_f32_16x16x32_bf16 v[72:75], v[124:127], v[186:189], v[72:75]
	v_mfma_f32_16x16x32_bf16 v[140:143], v[112:115], v[164:167], v[140:143]
	v_mfma_f32_16x16x32_bf16 v[136:139], v[132:135], v[164:167], v[136:139]
	v_mfma_f32_16x16x32_bf16 v[116:119], v[112:115], v[172:175], v[116:119]
	v_mfma_f32_16x16x32_bf16 v[108:111], v[132:135], v[172:175], v[108:111]
	v_mfma_f32_16x16x32_bf16 v[92:95], v[112:115], v[182:185], v[92:95]
	v_mfma_f32_16x16x32_bf16 v[88:91], v[132:135], v[182:185], v[88:91]
	v_mfma_f32_16x16x32_bf16 v[76:79], v[112:115], v[190:193], v[76:79]
	v_mfma_f32_16x16x32_bf16 v[72:75], v[132:135], v[190:193], v[72:75]
	v_mfma_f32_16x16x32_bf16 v[128:131], v[144:147], v[160:163], v[128:131]
	v_mfma_f32_16x16x32_bf16 v[120:123], v[152:155], v[160:163], v[120:123]
	v_mfma_f32_16x16x32_bf16 v[100:103], v[144:147], v[168:171], v[100:103]
	v_mfma_f32_16x16x32_bf16 v[96:99], v[152:155], v[168:171], v[96:99]
	v_mfma_f32_16x16x32_bf16 v[84:87], v[144:147], v[178:181], v[84:87]
	v_mfma_f32_16x16x32_bf16 v[80:83], v[152:155], v[178:181], v[80:83]
	v_mfma_f32_16x16x32_bf16 v[68:71], v[144:147], v[186:189], v[68:71]
	v_mfma_f32_16x16x32_bf16 v[64:67], v[152:155], v[186:189], v[64:67]
	v_mfma_f32_16x16x32_bf16 v[128:131], v[148:151], v[164:167], v[128:131]
	v_mfma_f32_16x16x32_bf16 v[120:123], v[156:159], v[164:167], v[120:123]
	v_mfma_f32_16x16x32_bf16 v[100:103], v[148:151], v[172:175], v[100:103]
	v_mfma_f32_16x16x32_bf16 v[96:99], v[156:159], v[172:175], v[96:99]
	v_mfma_f32_16x16x32_bf16 v[84:87], v[148:151], v[182:185], v[84:87]
	v_mfma_f32_16x16x32_bf16 v[80:83], v[156:159], v[182:185], v[80:83]
	v_mfma_f32_16x16x32_bf16 v[68:71], v[148:151], v[190:193], v[68:71]
	v_mfma_f32_16x16x32_bf16 v[64:67], v[156:159], v[190:193], v[64:67]
	s_barrier
; #define PG8_STAGE(bufoff, gbase, voff) do { _Pragma("unroll") for (int _i = 0; _i < 2; ++_i) \
;         __builtin_amdgcn_global_load_lds((const unsigned*)((const char*)(gbase) + (voff)[_i]), (PG8_LAS unsigned*)(lds + (bufoff) + ldsw + _i * 8192), 16, 0, 0); } while (0)
; #define PG8_LDA(dst, b, h) do { _Pragma("unroll") for (int m = 0; m < 4; ++m) _Pragma("unroll") for (int k = 0; k < 2; ++k) dst[m][k] = *(const PG8_LAS bf16x8*)(lds + PG8_SA(b, h) + aoff + m * 2048 + k * 1024); } while (0)
; #define PG8_MMA(ai, bj, At, Bt) do { __builtin_amdgcn_s_setprio(1); _Pragma("unroll") for (int m = 0; m < 4; ++m) _Pragma("unroll") for (int n = 0; n < 2; ++n) _Pragma("unroll") for (int k = 0; k < 2; ++k) \
;         acc[ai][bj][m][n] = __builtin_amdgcn_mfma_f32_16x16x32_bf16(Bt[n][k], At[m][k], acc[ai][bj][m][n], 0, 0, 0); __builtin_amdgcn_s_setprio(0); } while (0)
; #define PG8_WAIT_V(n) asm volatile("s_waitcnt vmcnt(" #n ")" ::: "memory")
; #define PG8_WAIT_L(n) asm volatile("s_waitcnt lgkmcnt(" #n ")" ::: "memory")
; #define PG8_BAR __builtin_amdgcn_s_barrier()
; #define PG8_SCHED __builtin_amdgcn_sched_barrier(0)
; template <class Epi, class Sched, bool ALIGN_EPI = false, bool SP2 = false>
; __device__ __forceinline__ void gemm_phase(PG8_LAS unsigned char* lds, const Gemm g, const Sched& S, const Epi& E, const int wid_) {
;     ...
;             PG8_LDA(At, 1, 1); PG8_STAGE(PG8_SB(1, 0), b3, voffB); PG8_STAGE(PG8_SB(1, 1), b3 + hstepB, voffB); PG8_STAGE(PG8_SA(1, 0), a3, voffA);
;             PG8_WAIT_V(8); PG8_WAIT_L(0); PG8_BAR; PG8_MMA(1, 0, At, B0); PG8_MMA(1, 1, At, B1); PG8_BAR; PG8_SCHED;
;     ...
;         if constexpr (ALIGN_EPI) { if (wr == 0) PG8_BAR; }
	s_add_i32 s8, s39, s33
	v_lshl_add_u64 v[194:195], v[194:195], 0, s[66:67]
	s_mov_b32 m0, s8
	ds_read_b128 v[160:163], v247 offset:49152
	ds_read_b128 v[164:167], v247 offset:50176
	ds_read_b128 v[168:171], v247 offset:51200
	ds_read_b128 v[172:175], v247 offset:52224
	ds_read_b128 v[178:181], v247 offset:53248
	ds_read_b128 v[182:185], v247 offset:54272
	ds_read_b128 v[186:189], v247 offset:55296
	ds_read_b128 v[190:193], v247 offset:56320
	global_load_lds_dwordx4 v[194:195], off
	v_lshl_add_u64 v[194:195], v[196:197], 0, s[66:67]
	s_add_i32 m0, s8, 0x2000
	s_add_i32 s8, s85, s33
	global_load_lds_dwordx4 v[194:195], off
	v_lshl_add_u64 v[194:195], v[198:199], 0, s[66:67]
	s_mov_b32 m0, s8
	s_nop 0
	global_load_lds_dwordx4 v[194:195], off
	v_lshl_add_u64 v[194:195], v[200:201], 0, s[66:67]
	s_add_i32 m0, s8, 0x2000
	s_nop 0
	global_load_lds_dwordx4 v[194:195], off
	v_lshl_add_u64 v[194:195], v[218:219], 0, s[66:67]
	s_mov_b32 m0, s68
	s_nop 0
	global_load_lds_dwordx4 v[194:195], off
	v_lshl_add_u64 v[194:195], v[220:221], 0, s[66:67]
	s_mov_b32 m0, s69
	s_nop 0
	global_load_lds_dwordx4 v[194:195], off
	s_waitcnt vmcnt(8)
	s_waitcnt lgkmcnt(0)
	s_barrier
	s_waitcnt lgkmcnt(0)
	v_mfma_f32_16x16x32_bf16 v[60:63], v[104:107], v[160:163], v[60:63]
	v_mfma_f32_16x16x32_bf16 v[56:59], v[124:127], v[160:163], v[56:59]
	v_mfma_f32_16x16x32_bf16 v[44:47], v[104:107], v[168:171], v[44:47]
	v_mfma_f32_16x16x32_bf16 v[40:43], v[124:127], v[168:171], v[40:43]
	v_mfma_f32_16x16x32_bf16 v[28:31], v[104:107], v[178:181], v[28:31]
	v_mfma_f32_16x16x32_bf16 v[24:27], v[124:127], v[178:181], v[24:27]
	v_mfma_f32_16x16x32_bf16 v[12:15], v[104:107], v[186:189], v[12:15]
	v_mfma_f32_16x16x32_bf16 v[8:11], v[124:127], v[186:189], v[8:11]
	v_mfma_f32_16x16x32_bf16 v[60:63], v[112:115], v[164:167], v[60:63]
	v_mfma_f32_16x16x32_bf16 v[56:59], v[132:135], v[164:167], v[56:59]
	v_mfma_f32_16x16x32_bf16 v[44:47], v[112:115], v[172:175], v[44:47]
	v_mfma_f32_16x16x32_bf16 v[40:43], v[132:135], v[172:175], v[40:43]
	v_mfma_f32_16x16x32_bf16 v[28:31], v[112:115], v[182:185], v[28:31]
	v_mfma_f32_16x16x32_bf16 v[24:27], v[132:135], v[182:185], v[24:27]
	v_mfma_f32_16x16x32_bf16 v[12:15], v[112:115], v[190:193], v[12:15]
	v_mfma_f32_16x16x32_bf16 v[8:11], v[132:135], v[190:193], v[8:11]
	v_mfma_f32_16x16x32_bf16 v[52:55], v[144:147], v[160:163], v[52:55]
	v_mfma_f32_16x16x32_bf16 v[48:51], v[152:155], v[160:163], v[48:51]
	v_mfma_f32_16x16x32_bf16 v[36:39], v[144:147], v[168:171], v[36:39]
	v_mfma_f32_16x16x32_bf16 v[32:35], v[152:155], v[168:171], v[32:35]
	v_mfma_f32_16x16x32_bf16 v[20:23], v[144:147], v[178:181], v[20:23]
	v_mfma_f32_16x16x32_bf16 v[16:19], v[152:155], v[178:181], v[16:19]
	v_mfma_f32_16x16x32_bf16 v[4:7], v[144:147], v[186:189], v[4:7]
	v_mfma_f32_16x16x32_bf16 v[0:3], v[152:155], v[186:189], v[0:3]
	v_mfma_f32_16x16x32_bf16 v[52:55], v[148:151], v[164:167], v[52:55]
	v_mfma_f32_16x16x32_bf16 v[48:51], v[156:159], v[164:167], v[48:51]
	v_mfma_f32_16x16x32_bf16 v[36:39], v[148:151], v[172:175], v[36:39]
	v_mfma_f32_16x16x32_bf16 v[32:35], v[156:159], v[172:175], v[32:35]
	v_mfma_f32_16x16x32_bf16 v[20:23], v[148:151], v[182:185], v[20:23]
	v_mfma_f32_16x16x32_bf16 v[16:19], v[156:159], v[182:185], v[16:19]
	v_mfma_f32_16x16x32_bf16 v[4:7], v[148:151], v[190:193], v[4:7]
	v_mfma_f32_16x16x32_bf16 v[0:3], v[156:159], v[190:193], v[0:3]
	s_barrier
	s_add_u32 s11, s11, 0x100
	s_addc_u32 s76, s76, 0
	s_add_u32 s6, s6, 0x100
	s_addc_u32 s7, s7, 0
	s_cmp_ge_u32 s38, s71
	s_mov_b32 s8, s38
	s_cbranch_scc0 .LBB0_614
	s_and_b64 vcc, exec, s[36:37]
	s_cbranch_vccz .LBB0_617
	s_barrier
